# w_branch/w_out bf16 conversion moved from phase 0 into the layer-0 in-projection start slot of the 128 workgroups that used to sleep there
# speedup vs baseline: 1.0469x; 1.0059x over previous
.Lxmap_ok:
.LBB0_17:
	s_or_b64 exec, exec, s[0:1]
	s_mov_b64 s[0:1], 0
	s_add_u32 s6, s96, s0
	s_addc_u32 s7, s97, s1
	v_mov_b32_e32 v48, v197
	v_mov_b32_e32 v10, v197
	s_cmpk_gt_i32 s52, 0x87f
	s_cbranch_scc1 .LBB0_78
	s_cmpk_lt_i32 s52, 0x880
	s_cselect_b64 s[0:1], -1, 0
	s_cmpk_gt_i32 s52, 0x87f
	s_cbranch_scc0 .LBB0_20
	s_add_i32 s3, s52, 0xfffff780
	v_readlane_b32 s8, v253, 0
	s_cmpk_lt_u32 s3, 0x200
	s_mov_b32 s4, 0x10100000
	v_readlane_b32 s9, v253, 1
	v_readlane_b32 s12, v253, 4
	v_readlane_b32 s13, v253, 5
	v_readlane_b32 s14, v253, 6
	v_readlane_b32 s15, v253, 7
	s_cselect_b32 s4, s4, 0x10500000
	s_cselect_b32 s5, s13, s15
	s_cselect_b32 s8, s12, s14
	s_lshl_b32 s9, s3, 12
	v_readlane_b32 s10, v253, 2
	s_and_b32 s9, s9, 0x100000
	s_lshl_b32 s10, s9, 2
	s_add_u32 s12, s8, s10
	s_addc_u32 s13, s5, 0
	s_add_u32 s4, s6, s4
	s_addc_u32 s5, s7, 0
	s_lshl_b32 s8, s9, 1
	s_add_u32 s4, s4, s8
	v_readlane_b32 s11, v253, 3
	s_addc_u32 s5, s5, 0
	s_lshl_b32 s3, s3, 2
	s_and_b32 s8, s3, 0x3c0
	s_lshl_b32 s3, s52, 2
	s_mov_b64 s[14:15], 0x400
	s_mov_b32 s11, s8
	s_cbranch_execz .LBB0_21
	s_branch .LBB0_37

.LBB0_40:
	s_add_i32 s47, s47, s98
	s_cmpk_gt_i32 s47, 0x87f
	s_cselect_b64 s[16:17], -1, 0
	s_and_b64 vcc, exec, s[16:17]
	s_waitcnt vmcnt(1)
	ds_write2_b32 v15, v0, v1 offset1:1
	ds_write2_b32 v15, v2, v3 offset0:2 offset1:3
	s_waitcnt vmcnt(0)
	ds_write2_b32 v18, v4, v5 offset1:1
	ds_write2_b32 v19, v6, v7 offset1:1
	s_waitcnt lgkmcnt(0)
	s_barrier
	s_cbranch_vccnz .LBB0_59
	s_cmpk_lt_i32 s47, 0x880
	s_cselect_b64 s[14:15], -1, 0
	s_cmpk_gt_i32 s47, 0x87f
	s_mov_b64 s[26:27], -1
	s_cbranch_scc0 .LBB0_43
	s_add_i32 s18, s47, 0xfffff780
	v_readlane_b32 s20, v253, 0
	s_cmpk_lt_u32 s18, 0x200
	v_readlane_b32 s21, v253, 1
	v_readlane_b32 s24, v253, 4
	v_readlane_b32 s25, v253, 5
	v_readlane_b32 s26, v253, 6
	v_readlane_b32 s27, v253, 7
	s_cselect_b32 s18, s39, 0x10500000
	v_readlane_b32 s22, v253, 2
	s_cselect_b32 s19, s25, s27
	s_cselect_b32 s20, s24, s26
	s_and_b32 s21, s33, 0x100000
	s_lshl_b32 s22, s21, 2
	v_readlane_b32 s23, v253, 3
	s_add_u32 s22, s20, s22
	s_addc_u32 s23, s19, 0
	s_add_u32 s18, s6, s18
	s_addc_u32 s19, s7, 0
	s_lshl_b32 s20, s21, 1
	s_add_u32 s20, s18, s20
	s_addc_u32 s21, s19, 0
	s_add_i32 s18, s9, s3
	s_addk_i32 s18, 0xde00
	s_and_b32 s18, s18, 0x3c0
	s_mov_b64 s[26:27], 0

.LBB0_241:
	s_or_b64 exec, exec, s[0:1]
	v_readlane_b32 s2, v253, 26
	v_readlane_b32 s3, v253, 27
	s_mov_b64 s[0:1], 0
	s_andn2_b64 vcc, exec, s[2:3]
	s_waitcnt lgkmcnt(0)
	s_barrier
	s_cbranch_vccnz .LBB0_243
	v_readlane_b32 s2, v252, 23
	s_nop 3
	s_cmp_eq_u32 s2, 0
	s_cbranch_scc1 .Lcw_sleep
	v_readlane_b32 s28, v253, 4
	v_readlane_b32 s29, v253, 5
	v_readlane_b32 s30, v253, 6
	v_readlane_b32 s31, v253, 7
	v_lshrrev_b32_e32 v120, 4, v197
	v_and_b32_e32 v121, 15, v197
	v_lshlrev_b32_e32 v121, 2, v121
	v_lshl_add_u32 v122, v120, 10, v121
	v_lshlrev_b32_e32 v122, 2, v122
	v_mul_u32_u24_e32 v123, 0x41, v120
	v_add_u32_e32 v123, v123, v121
	v_lshlrev_b32_e32 v123, 2, v123
	v_lshrrev_b32_e32 v124, 3, v197
	v_and_b32_e32 v125, 7, v197
	v_lshlrev_b32_e32 v125, 3, v125
	v_bfe_u32 v127, v124, 2, 2
	v_lshlrev_b32_e32 v127, 3, v127
	v_bfe_u32 v136, v124, 4, 1
	v_lshl_add_u32 v127, v136, 2, v127
	v_and_b32_e32 v136, 3, v124
	v_add_u32_e32 v127, v127, v136
	v_and_b32_e32 v136, 32, v124
	v_add_u32_e32 v127, v127, v136
	v_mul_u32_u24_e32 v136, 0x41, v125
	v_add_u32_e32 v136, v136, v127
	v_lshlrev_b32_e32 v136, 2, v136
	v_lshl_add_u32 v137, v124, 10, v125
	v_lshlrev_b32_e32 v137, 1, v137
	s_sub_i32 s2, s52, 0x80
	s_add_i32 s4, s2, 0
	s_cmpk_lt_u32 s4, 0x200
	s_cselect_b32 s6, s28, s30
	s_cselect_b32 s7, s29, s31
	s_mov_b32 s16, 0x10500000
	s_cselect_b32 s16, 0x10100000, s16
	s_bfe_u32 s5, s4, 0x10008
	s_lshl_b32 s3, s5, 22
	s_add_u32 s6, s6, s3
	s_addc_u32 s7, s7, 0
	s_lshl_b32 s3, s5, 21
	s_add_i32 s16, s16, s3
	s_and_b32 s3, s4, 15
	s_bfe_u32 s5, s4, 0x40004
	s_lshl_b32 s17, s3, 18
	s_lshl_b32 s20, s5, 8
	s_add_i32 s17, s17, s20
	s_add_u32 s6, s6, s17
	s_addc_u32 s7, s7, 0
	s_add_u32 s12, s6, 0x20000
	s_addc_u32 s13, s7, 0
	s_lshl_b32 s17, s5, 17
	s_lshl_b32 s20, s3, 7
	s_add_i32 s17, s17, s20
	s_add_i32 s16, s16, s17
	s_add_u32 s16, s96, s16
	s_addc_u32 s17, s97, 0
	global_load_dwordx4 v[140:143], v122, s[6:7]
	global_load_dwordx4 v[150:153], v122, s[12:13]
	s_waitcnt vmcnt(0)
	ds_write_b32 v123, v140 offset:0
	ds_write_b32 v123, v141 offset:4
	ds_write_b32 v123, v142 offset:8
	ds_write_b32 v123, v143 offset:12
	ds_write_b32 v123, v150 offset:8320
	ds_write_b32 v123, v151 offset:8324
	ds_write_b32 v123, v152 offset:8328
	ds_write_b32 v123, v153 offset:8332
	s_waitcnt lgkmcnt(0)
	s_barrier
	s_mov_b64 s[26:27], s[16:17]
	s_add_i32 s4, s2, 128
	s_cmpk_lt_u32 s4, 0x200
	s_cselect_b32 s6, s28, s30
	s_cselect_b32 s7, s29, s31
	s_mov_b32 s16, 0x10500000
	s_cselect_b32 s16, 0x10100000, s16
	s_bfe_u32 s5, s4, 0x10008
	s_lshl_b32 s3, s5, 22
	s_add_u32 s6, s6, s3
	s_addc_u32 s7, s7, 0
	s_lshl_b32 s3, s5, 21
	s_add_i32 s16, s16, s3
	s_and_b32 s3, s4, 15
	s_bfe_u32 s5, s4, 0x40004
	s_lshl_b32 s17, s3, 18
	s_lshl_b32 s20, s5, 8
	s_add_i32 s17, s17, s20
	s_add_u32 s6, s6, s17
	s_addc_u32 s7, s7, 0
	s_add_u32 s12, s6, 0x20000
	s_addc_u32 s13, s7, 0
	s_lshl_b32 s17, s5, 17
	s_lshl_b32 s20, s3, 7
	s_add_i32 s17, s17, s20
	s_add_i32 s16, s16, s17
	s_add_u32 s16, s96, s16
	s_addc_u32 s17, s97, 0
	global_load_dwordx4 v[140:143], v122, s[6:7]
	global_load_dwordx4 v[150:153], v122, s[12:13]
	ds_read_b32 v154, v136 offset:0
	ds_read_b32 v155, v136 offset:260
	ds_read_b32 v156, v136 offset:520
	ds_read_b32 v157, v136 offset:780
	ds_read_b32 v158, v136 offset:1040
	ds_read_b32 v159, v136 offset:1300
	ds_read_b32 v160, v136 offset:1560
	ds_read_b32 v161, v136 offset:1820
	s_waitcnt lgkmcnt(0)
	v_cvt_pk_bf16_f32 v204, v154, v155
	v_cvt_pk_bf16_f32 v205, v156, v157
	v_cvt_pk_bf16_f32 v206, v158, v159
	v_cvt_pk_bf16_f32 v207, v160, v161
	global_store_dwordx4 v137, v[204:207], s[26:27]
	s_barrier
	s_waitcnt vmcnt(0)
	ds_write_b32 v123, v140 offset:0
	ds_write_b32 v123, v141 offset:4
	ds_write_b32 v123, v142 offset:8
	ds_write_b32 v123, v143 offset:12
	ds_write_b32 v123, v150 offset:8320
	ds_write_b32 v123, v151 offset:8324
	ds_write_b32 v123, v152 offset:8328
	ds_write_b32 v123, v153 offset:8332
	s_waitcnt lgkmcnt(0)
	s_barrier
	s_mov_b64 s[26:27], s[16:17]
	s_add_i32 s4, s2, 256
	s_cmpk_lt_u32 s4, 0x200
	s_cselect_b32 s6, s28, s30
	s_cselect_b32 s7, s29, s31
	s_mov_b32 s16, 0x10500000
	s_cselect_b32 s16, 0x10100000, s16
	s_bfe_u32 s5, s4, 0x10008
	s_lshl_b32 s3, s5, 22
	s_add_u32 s6, s6, s3
	s_addc_u32 s7, s7, 0
	s_lshl_b32 s3, s5, 21
	s_add_i32 s16, s16, s3
	s_and_b32 s3, s4, 15
	s_bfe_u32 s5, s4, 0x40004
	s_lshl_b32 s17, s3, 18
	s_lshl_b32 s20, s5, 8
	s_add_i32 s17, s17, s20
	s_add_u32 s6, s6, s17
	s_addc_u32 s7, s7, 0
	s_add_u32 s12, s6, 0x20000
	s_addc_u32 s13, s7, 0
	s_lshl_b32 s17, s5, 17
	s_lshl_b32 s20, s3, 7
	s_add_i32 s17, s17, s20
	s_add_i32 s16, s16, s17
	s_add_u32 s16, s96, s16
	s_addc_u32 s17, s97, 0
	global_load_dwordx4 v[140:143], v122, s[6:7]
	global_load_dwordx4 v[150:153], v122, s[12:13]
	ds_read_b32 v154, v136 offset:0
	ds_read_b32 v155, v136 offset:260
	ds_read_b32 v156, v136 offset:520
	ds_read_b32 v157, v136 offset:780
	ds_read_b32 v158, v136 offset:1040
	ds_read_b32 v159, v136 offset:1300
	ds_read_b32 v160, v136 offset:1560
	ds_read_b32 v161, v136 offset:1820
	s_waitcnt lgkmcnt(0)
	v_cvt_pk_bf16_f32 v204, v154, v155
	v_cvt_pk_bf16_f32 v205, v156, v157
	v_cvt_pk_bf16_f32 v206, v158, v159
	v_cvt_pk_bf16_f32 v207, v160, v161
	global_store_dwordx4 v137, v[204:207], s[26:27]
	s_barrier
	s_waitcnt vmcnt(0)
	ds_write_b32 v123, v140 offset:0
	ds_write_b32 v123, v141 offset:4
	ds_write_b32 v123, v142 offset:8
	ds_write_b32 v123, v143 offset:12
	ds_write_b32 v123, v150 offset:8320
	ds_write_b32 v123, v151 offset:8324
	ds_write_b32 v123, v152 offset:8328
	ds_write_b32 v123, v153 offset:8332
	s_waitcnt lgkmcnt(0)
	s_barrier
	s_mov_b64 s[26:27], s[16:17]
	s_add_i32 s4, s2, 384
	s_cmpk_lt_u32 s4, 0x200
	s_cselect_b32 s6, s28, s30
	s_cselect_b32 s7, s29, s31
	s_mov_b32 s16, 0x10500000
	s_cselect_b32 s16, 0x10100000, s16
	s_bfe_u32 s5, s4, 0x10008
	s_lshl_b32 s3, s5, 22
	s_add_u32 s6, s6, s3
	s_addc_u32 s7, s7, 0
	s_lshl_b32 s3, s5, 21
	s_add_i32 s16, s16, s3
	s_and_b32 s3, s4, 15
	s_bfe_u32 s5, s4, 0x40004
	s_lshl_b32 s17, s3, 18
	s_lshl_b32 s20, s5, 8
	s_add_i32 s17, s17, s20
	s_add_u32 s6, s6, s17
	s_addc_u32 s7, s7, 0
	s_add_u32 s12, s6, 0x20000
	s_addc_u32 s13, s7, 0
	s_lshl_b32 s17, s5, 17
	s_lshl_b32 s20, s3, 7
	s_add_i32 s17, s17, s20
	s_add_i32 s16, s16, s17
	s_add_u32 s16, s96, s16
	s_addc_u32 s17, s97, 0
	global_load_dwordx4 v[140:143], v122, s[6:7]
	global_load_dwordx4 v[150:153], v122, s[12:13]
	ds_read_b32 v154, v136 offset:0
	ds_read_b32 v155, v136 offset:260
	ds_read_b32 v156, v136 offset:520
	ds_read_b32 v157, v136 offset:780
	ds_read_b32 v158, v136 offset:1040
	ds_read_b32 v159, v136 offset:1300
	ds_read_b32 v160, v136 offset:1560
	ds_read_b32 v161, v136 offset:1820
	s_waitcnt lgkmcnt(0)
	v_cvt_pk_bf16_f32 v204, v154, v155
	v_cvt_pk_bf16_f32 v205, v156, v157
	v_cvt_pk_bf16_f32 v206, v158, v159
	v_cvt_pk_bf16_f32 v207, v160, v161
	global_store_dwordx4 v137, v[204:207], s[26:27]
	s_barrier
	s_waitcnt vmcnt(0)
	ds_write_b32 v123, v140 offset:0
	ds_write_b32 v123, v141 offset:4
	ds_write_b32 v123, v142 offset:8
	ds_write_b32 v123, v143 offset:12
	ds_write_b32 v123, v150 offset:8320
	ds_write_b32 v123, v151 offset:8324
	ds_write_b32 v123, v152 offset:8328
	ds_write_b32 v123, v153 offset:8332
	s_waitcnt lgkmcnt(0)
	s_barrier
	s_mov_b64 s[26:27], s[16:17]
	s_add_i32 s4, s2, 512
	s_cmpk_lt_u32 s4, 0x200
	s_cselect_b32 s6, s28, s30
	s_cselect_b32 s7, s29, s31
	s_mov_b32 s16, 0x10500000
	s_cselect_b32 s16, 0x10100000, s16
	s_bfe_u32 s5, s4, 0x10008
	s_lshl_b32 s3, s5, 22
	s_add_u32 s6, s6, s3
	s_addc_u32 s7, s7, 0
	s_lshl_b32 s3, s5, 21
	s_add_i32 s16, s16, s3
	s_and_b32 s3, s4, 15
	s_bfe_u32 s5, s4, 0x40004
	s_lshl_b32 s17, s3, 18
	s_lshl_b32 s20, s5, 8
	s_add_i32 s17, s17, s20
	s_add_u32 s6, s6, s17
	s_addc_u32 s7, s7, 0
	s_add_u32 s12, s6, 0x20000
	s_addc_u32 s13, s7, 0
	s_lshl_b32 s17, s5, 17
	s_lshl_b32 s20, s3, 7
	s_add_i32 s17, s17, s20
	s_add_i32 s16, s16, s17
	s_add_u32 s16, s96, s16
	s_addc_u32 s17, s97, 0
	global_load_dwordx4 v[140:143], v122, s[6:7]
	global_load_dwordx4 v[150:153], v122, s[12:13]
	ds_read_b32 v154, v136 offset:0
	ds_read_b32 v155, v136 offset:260
	ds_read_b32 v156, v136 offset:520
	ds_read_b32 v157, v136 offset:780
	ds_read_b32 v158, v136 offset:1040
	ds_read_b32 v159, v136 offset:1300
	ds_read_b32 v160, v136 offset:1560
	ds_read_b32 v161, v136 offset:1820
	s_waitcnt lgkmcnt(0)
	v_cvt_pk_bf16_f32 v204, v154, v155
	v_cvt_pk_bf16_f32 v205, v156, v157
	v_cvt_pk_bf16_f32 v206, v158, v159
	v_cvt_pk_bf16_f32 v207, v160, v161
	global_store_dwordx4 v137, v[204:207], s[26:27]
	s_barrier
	s_waitcnt vmcnt(0)
	ds_write_b32 v123, v140 offset:0
	ds_write_b32 v123, v141 offset:4
	ds_write_b32 v123, v142 offset:8
	ds_write_b32 v123, v143 offset:12
	ds_write_b32 v123, v150 offset:8320
	ds_write_b32 v123, v151 offset:8324
	ds_write_b32 v123, v152 offset:8328
	ds_write_b32 v123, v153 offset:8332
	s_waitcnt lgkmcnt(0)
	s_barrier
	s_mov_b64 s[26:27], s[16:17]
	s_add_i32 s4, s2, 640
	s_cmpk_lt_u32 s4, 0x200
	s_cselect_b32 s6, s28, s30
	s_cselect_b32 s7, s29, s31
	s_mov_b32 s16, 0x10500000
	s_cselect_b32 s16, 0x10100000, s16
	s_bfe_u32 s5, s4, 0x10008
	s_lshl_b32 s3, s5, 22
	s_add_u32 s6, s6, s3
	s_addc_u32 s7, s7, 0
	s_lshl_b32 s3, s5, 21
	s_add_i32 s16, s16, s3
	s_and_b32 s3, s4, 15
	s_bfe_u32 s5, s4, 0x40004
	s_lshl_b32 s17, s3, 18
	s_lshl_b32 s20, s5, 8
	s_add_i32 s17, s17, s20
	s_add_u32 s6, s6, s17
	s_addc_u32 s7, s7, 0
	s_add_u32 s12, s6, 0x20000
	s_addc_u32 s13, s7, 0
	s_lshl_b32 s17, s5, 17
	s_lshl_b32 s20, s3, 7
	s_add_i32 s17, s17, s20
	s_add_i32 s16, s16, s17
	s_add_u32 s16, s96, s16
	s_addc_u32 s17, s97, 0
	global_load_dwordx4 v[140:143], v122, s[6:7]
	global_load_dwordx4 v[150:153], v122, s[12:13]
	ds_read_b32 v154, v136 offset:0
	ds_read_b32 v155, v136 offset:260
	ds_read_b32 v156, v136 offset:520
	ds_read_b32 v157, v136 offset:780
	ds_read_b32 v158, v136 offset:1040
	ds_read_b32 v159, v136 offset:1300
	ds_read_b32 v160, v136 offset:1560
	ds_read_b32 v161, v136 offset:1820
	s_waitcnt lgkmcnt(0)
	v_cvt_pk_bf16_f32 v204, v154, v155
	v_cvt_pk_bf16_f32 v205, v156, v157
	v_cvt_pk_bf16_f32 v206, v158, v159
	v_cvt_pk_bf16_f32 v207, v160, v161
	global_store_dwordx4 v137, v[204:207], s[26:27]
	s_barrier
	s_waitcnt vmcnt(0)
	ds_write_b32 v123, v140 offset:0
	ds_write_b32 v123, v141 offset:4
	ds_write_b32 v123, v142 offset:8
	ds_write_b32 v123, v143 offset:12
	ds_write_b32 v123, v150 offset:8320
	ds_write_b32 v123, v151 offset:8324
	ds_write_b32 v123, v152 offset:8328
	ds_write_b32 v123, v153 offset:8332
	s_waitcnt lgkmcnt(0)
	s_barrier
	s_mov_b64 s[26:27], s[16:17]
	s_add_i32 s4, s2, 768
	s_cmpk_lt_u32 s4, 0x200
	s_cselect_b32 s6, s28, s30
	s_cselect_b32 s7, s29, s31
	s_mov_b32 s16, 0x10500000
	s_cselect_b32 s16, 0x10100000, s16
	s_bfe_u32 s5, s4, 0x10008
	s_lshl_b32 s3, s5, 22
	s_add_u32 s6, s6, s3
	s_addc_u32 s7, s7, 0
	s_lshl_b32 s3, s5, 21
	s_add_i32 s16, s16, s3
	s_and_b32 s3, s4, 15
	s_bfe_u32 s5, s4, 0x40004
	s_lshl_b32 s17, s3, 18
	s_lshl_b32 s20, s5, 8
	s_add_i32 s17, s17, s20
	s_add_u32 s6, s6, s17
	s_addc_u32 s7, s7, 0
	s_add_u32 s12, s6, 0x20000
	s_addc_u32 s13, s7, 0
	s_lshl_b32 s17, s5, 17
	s_lshl_b32 s20, s3, 7
	s_add_i32 s17, s17, s20
	s_add_i32 s16, s16, s17
	s_add_u32 s16, s96, s16
	s_addc_u32 s17, s97, 0
	global_load_dwordx4 v[140:143], v122, s[6:7]
	global_load_dwordx4 v[150:153], v122, s[12:13]
	ds_read_b32 v154, v136 offset:0
	ds_read_b32 v155, v136 offset:260
	ds_read_b32 v156, v136 offset:520
	ds_read_b32 v157, v136 offset:780
	ds_read_b32 v158, v136 offset:1040
	ds_read_b32 v159, v136 offset:1300
	ds_read_b32 v160, v136 offset:1560
	ds_read_b32 v161, v136 offset:1820
	s_waitcnt lgkmcnt(0)
	v_cvt_pk_bf16_f32 v204, v154, v155
	v_cvt_pk_bf16_f32 v205, v156, v157
	v_cvt_pk_bf16_f32 v206, v158, v159
	v_cvt_pk_bf16_f32 v207, v160, v161
	global_store_dwordx4 v137, v[204:207], s[26:27]
	s_barrier
	s_waitcnt vmcnt(0)
	ds_write_b32 v123, v140 offset:0
	ds_write_b32 v123, v141 offset:4
	ds_write_b32 v123, v142 offset:8
	ds_write_b32 v123, v143 offset:12
	ds_write_b32 v123, v150 offset:8320
	ds_write_b32 v123, v151 offset:8324
	ds_write_b32 v123, v152 offset:8328
	ds_write_b32 v123, v153 offset:8332
	s_waitcnt lgkmcnt(0)
	s_barrier
	s_mov_b64 s[26:27], s[16:17]
	s_add_i32 s4, s2, 896
	s_cmpk_lt_u32 s4, 0x200
	s_cselect_b32 s6, s28, s30
	s_cselect_b32 s7, s29, s31
	s_mov_b32 s16, 0x10500000
	s_cselect_b32 s16, 0x10100000, s16
	s_bfe_u32 s5, s4, 0x10008
	s_lshl_b32 s3, s5, 22
	s_add_u32 s6, s6, s3
	s_addc_u32 s7, s7, 0
	s_lshl_b32 s3, s5, 21
	s_add_i32 s16, s16, s3
	s_and_b32 s3, s4, 15
	s_bfe_u32 s5, s4, 0x40004
	s_lshl_b32 s17, s3, 18
	s_lshl_b32 s20, s5, 8
	s_add_i32 s17, s17, s20
	s_add_u32 s6, s6, s17
	s_addc_u32 s7, s7, 0
	s_add_u32 s12, s6, 0x20000
	s_addc_u32 s13, s7, 0
	s_lshl_b32 s17, s5, 17
	s_lshl_b32 s20, s3, 7
	s_add_i32 s17, s17, s20
	s_add_i32 s16, s16, s17
	s_add_u32 s16, s96, s16
	s_addc_u32 s17, s97, 0
	global_load_dwordx4 v[140:143], v122, s[6:7]
	global_load_dwordx4 v[150:153], v122, s[12:13]
	ds_read_b32 v154, v136 offset:0
	ds_read_b32 v155, v136 offset:260
	ds_read_b32 v156, v136 offset:520
	ds_read_b32 v157, v136 offset:780
	ds_read_b32 v158, v136 offset:1040
	ds_read_b32 v159, v136 offset:1300
	ds_read_b32 v160, v136 offset:1560
	ds_read_b32 v161, v136 offset:1820
	s_waitcnt lgkmcnt(0)
	v_cvt_pk_bf16_f32 v204, v154, v155
	v_cvt_pk_bf16_f32 v205, v156, v157
	v_cvt_pk_bf16_f32 v206, v158, v159
	v_cvt_pk_bf16_f32 v207, v160, v161
	global_store_dwordx4 v137, v[204:207], s[26:27]
	s_barrier
	s_waitcnt vmcnt(0)
	ds_write_b32 v123, v140 offset:0
	ds_write_b32 v123, v141 offset:4
	ds_write_b32 v123, v142 offset:8
	ds_write_b32 v123, v143 offset:12
	ds_write_b32 v123, v150 offset:8320
	ds_write_b32 v123, v151 offset:8324
	ds_write_b32 v123, v152 offset:8328
	ds_write_b32 v123, v153 offset:8332
	s_waitcnt lgkmcnt(0)
	s_barrier
	s_mov_b64 s[26:27], s[16:17]
	ds_read_b32 v154, v136 offset:0
	ds_read_b32 v155, v136 offset:260
	ds_read_b32 v156, v136 offset:520
	ds_read_b32 v157, v136 offset:780
	ds_read_b32 v158, v136 offset:1040
	ds_read_b32 v159, v136 offset:1300
	ds_read_b32 v160, v136 offset:1560
	ds_read_b32 v161, v136 offset:1820
	s_waitcnt lgkmcnt(0)
	v_cvt_pk_bf16_f32 v204, v154, v155
	v_cvt_pk_bf16_f32 v205, v156, v157
	v_cvt_pk_bf16_f32 v206, v158, v159
	v_cvt_pk_bf16_f32 v207, v160, v161
	global_store_dwordx4 v137, v[204:207], s[26:27]
	s_barrier
	s_sleep 0x7f
	s_branch .LBB0_243
.Lcw_sleep:
	s_sleep 0x7f
	s_sleep 0x7f
	s_sleep 0x7f
	s_sleep 0x7f
